# speedup vs baseline: 1.0872x; 1.0312x over previous
; DEV int otid() { int t = threadIdx.x; asm volatile("" : "+v"(t)); return t; }
; template <bool SWAP, class RowA, class Epi>
; DEV void gemm_tile(unsigned char* smem, RowA rowA, const bf16_t* Bt, int K, Epi epi) {
;   const int tid = otid(), lane = tid & 63, wid = tid >> 6, wr = wid >> 1, wc = wid & 1, fr = lane & 15, fq = lane >> 4;
;   const int r0 = tid >> 2;
;   const int a_w = (r0 >> 2) & 3, g_w = (((a_w ^ (a_w >> 1)) & 1) << 1) | (a_w >> 1);
;   const int cc = ((tid & 3) ^ g_w) * 8;
;   const int a_r = (fr >> 2) & 3, g_r = (((a_r ^ (a_r >> 1)) & 1) << 1) | (a_r >> 1);
;   const int rdoff = fr * 64 + ((fq ^ g_r) * 16);
;   const bf16_t* a0 = rowA(r0) + cc;
;   const bf16_t* a1 = rowA(r0 + 64) + cc;
;   const bf16_t* b0 = Bt + (size_t)r0 * K + cc;
;   const bf16_t* b1 = Bt + (size_t)(r0 + 64) * K + cc;
;   f32x4 acc[4][4];
; #pragma unroll
;   for (int m = 0; m < 4; ++m)
; #pragma unroll
;     for (int n = 0; n < 4; ++n) acc[m][n] = f32x4{0.f, 0.f, 0.f, 0.f};
;   const int nk = K / 32;
;   auto stage = [&](int kt, int buf) {
;     unsigned char* SA = smem + buf * 16384 + tid * 16;
;     unsigned char* SB = SA + 8192;
;     const int ko = kt * 32;
;     glds16(a0 + ko, SA); glds16(a1 + ko, SA + 4096);
;     glds16(b0 + ko, SB); glds16(b1 + ko, SB + 4096);
;   };
;   stage(0, 0);
; DEV void phase_moe1(const Params& p, int l, unsigned char* smem) {
;     ...
;   for (int t = blockIdx.x; t < ntile; t += gridDim.x) {
;     int e = 0;
;     while (s_tile[e + 1] <= t) ++e;
;     const int local = t - s_tile[e], cnt = s_cnt[e], nmt = (cnt + 127) >> 7;
;     const int mt = local / NTN_, nt = local % NTN_;
;     const int* lst = p.list + e * NTOK;
;     const int rowoff = s_off[e];
;     const float* bgu = p.b_gu + (size_t)(l * 32 + e) * 2048;
;     gemm_tile<true>(smem, [&](int r) { int i = min(mt * 128 + r, cnt - 1); return p.hbuf + (size_t)lst[i] * 1024; },
;       p.wgu_t + ((size_t)(l * 32 + e) * 2048 + nt * 128) * 1024, 1024,
.LBB0_648:
	v_mov_b32_e32 v0, s1
	ds_read_b32 v0, v0 offset:33032
	s_add_i32 s0, s0, 1
	s_add_i32 s1, s1, 4
	s_add_u32 s4, s4, 0x400000
	s_addc_u32 s5, s5, 0
	s_waitcnt lgkmcnt(0)
	v_cmp_ge_i32_e32 vcc, s23, v0
	s_cbranch_vccnz .LBB0_648
	v_mov_b32_e32 v0, s1
	ds_read_b32 v1, v0 offset:33024
	s_mul_i32 s18, s0, 0x4200
	s_lshl_b64 s[6:7], s[18:19], 2
	v_add_u32_e32 v0, 0x8000, v0
	ds_read2_b32 v[76:77], v0 offset1:32
	s_waitcnt lgkmcnt(1)
	v_readfirstlane_b32 s1, v1
	s_sub_i32 s1, s23, s1
	s_ashr_i32 s8, s1, 31
	s_lshr_b32 s8, s8, 28
	s_add_i32 s11, s1, s8
	s_and_b32 s8, s11, -16
	s_sub_i32 s10, s1, s8
	s_add_u32 s20, s68, s6
	s_addc_u32 s21, s69, s7
	s_mov_b32 s1, s19
	s_lshl_b32 s6, s10, 7
	s_lshl_b64 s[0:1], s[0:1], 11
	s_ashr_i32 s7, s6, 31
	s_add_u32 s8, s0, s6
	s_addc_u32 s9, s1, s7
	s_lshl_b64 s[8:9], s[8:9], 11
	s_add_u32 s8, s36, s8
	s_addc_u32 s9, s37, s9
	v_mov_b32_e32 v14, v122
	s_lshl_b32 s11, s11, 3
	s_and_b32 s11, s11, 0xffffff80
	v_ashrrev_i32_e32 v0, 2, v14
	v_add_u32_e32 v1, s11, v0
	s_waitcnt lgkmcnt(0)
	v_add_u32_e32 v5, -1, v76
	v_add_u32_e32 v4, 64, v0
	v_min_i32_e32 v2, v1, v5
	v_add_u32_e32 v1, s11, v4
	v_min_i32_e32 v6, v1, v5
	v_ashrrev_i32_e32 v3, 31, v2
	v_ashrrev_i32_e32 v7, 31, v6
	v_lshl_add_u64 v[2:3], v[2:3], 2, s[20:21]
	v_lshl_add_u64 v[6:7], v[6:7], 2, s[20:21]
	global_load_dword v2, v[2:3], off
	s_nop 0
	global_load_dword v6, v[6:7], off
	v_lshrrev_b32_e32 v132, 3, v122
	v_add_u32_e32 v132, s11, v132
	v_min_i32_e32 v134, v132, v5
	v_ashrrev_i32_e32 v135, 31, v134
	v_lshl_add_u64 v[134:135], v[134:135], 2, s[20:21]
	global_load_dword v128, v[134:135], off
	v_add_u32_e32 v136, 32, v132
	v_min_i32_e32 v134, v136, v5
	v_ashrrev_i32_e32 v135, 31, v134
	v_lshl_add_u64 v[134:135], v[134:135], 2, s[20:21]
	global_load_dword v129, v[134:135], off
	v_add_u32_e32 v136, 64, v132
	v_min_i32_e32 v134, v136, v5
	v_ashrrev_i32_e32 v135, 31, v134
	v_lshl_add_u64 v[134:135], v[134:135], 2, s[20:21]
	global_load_dword v130, v[134:135], off
	v_add_u32_e32 v136, 96, v132
	v_min_i32_e32 v134, v136, v5
	v_ashrrev_i32_e32 v135, 31, v134
	v_lshl_add_u64 v[134:135], v[134:135], 2, s[20:21]
	global_load_dword v131, v[134:135], off
	v_lshrrev_b32_e32 v1, 4, v14
	v_lshrrev_b32_e32 v3, 5, v14
	v_xor_b32_e32 v3, v1, v3
	v_lshlrev_b32_e32 v3, 1, v3
	v_bfe_u32 v7, v14, 5, 1
	v_and_b32_e32 v8, 3, v14
	v_and_b32_e32 v3, 2, v3
	v_lshrrev_b32_e32 v5, 2, v14
	v_lshrrev_b32_e32 v9, 3, v14
	v_bitop3_b32 v3, v3, v8, v7 bitop3:0x36
	v_lshlrev_b32_e32 v70, 4, v14
	v_xor_b32_e32 v5, v5, v9
	v_lshlrev_b32_e32 v72, 4, v3
	v_add_u32_e32 v9, 0x2000, v70
	v_add_u32_e32 v12, 0x3000, v70
	v_lshlrev_b32_e32 v13, 1, v5
	v_bfe_u32 v75, v14, 4, 2
	v_bfe_u32 v10, v14, 3, 1
	v_ashrrev_i32_e32 v1, 31, v0
	v_readfirstlane_b32 s18, v70
	v_add_u32_e32 v11, 0x1000, v70
	v_readfirstlane_b32 s21, v9
	v_readfirstlane_b32 s28, v12
	v_and_b32_e32 v9, 2, v13
	v_lshlrev_b64 v[0:1], 11, v[0:1]
	v_ashrrev_i32_e32 v5, 31, v4
	v_readfirstlane_b32 s20, v11
	v_bitop3_b32 v15, v9, v75, v10 bitop3:0x36
	s_mov_b32 m0, s18
	v_lshlrev_b64 v[4:5], 11, v[4:5]
	v_lshl_add_u64 v[8:9], s[8:9], 0, v[0:1]
	v_lshl_add_u64 v[4:5], s[8:9], 0, v[4:5]
	v_lshl_add_u64 v[8:9], v[8:9], 0, v[72:73]
	v_lshl_add_u64 v[4:5], v[4:5], 0, v[72:73]
	v_and_b32_e32 v79, 15, v14
	s_lshl_b64 s[6:7], s[6:7], 11
	v_lshl_add_u64 v[0:1], v[0:1], 0, s[6:7]
	v_bfe_u32 v74, v14, 6, 1
	v_ashrrev_i32_e32 v78, 7, v14
	v_or_b32_e32 v0, v0, v72
	v_lshlrev_b32_e32 v80, 12, v78
	v_lshlrev_b32_e32 v81, 12, v74
	v_lshl_add_u64 v[68:69], s[4:5], 0, v[0:1]
	s_mov_b32 s6, 0
	s_mov_b64 s[4:5], 0
	s_waitcnt vmcnt(1)
	v_ashrrev_i32_e32 v3, 31, v2
	s_waitcnt vmcnt(0)
	v_ashrrev_i32_e32 v7, 31, v6
	v_lshlrev_b64 v[2:3], 11, v[2:3]
	v_lshlrev_b64 v[6:7], 11, v[6:7]
	v_lshl_add_u64 v[12:13], s[46:47], 0, v[2:3]
	v_lshl_add_u64 v[10:11], s[46:47], 0, v[6:7]
	v_lshl_add_u64 v[12:13], v[12:13], 0, v[72:73]
	v_lshl_add_u64 v[10:11], v[10:11], 0, v[72:73]
	s_mov_b32 m0, s20
	v_or_b32_e32 v2, v2, v72
	s_mov_b32 m0, s21
	v_or_b32_e32 v6, v6, v72
	s_mov_b32 m0, s28
	v_lshl_add_u64 v[64:65], s[16:17], 0, v[2:3]
	v_lshlrev_b32_e32 v4, 6, v79
	v_lshl_or_b32 v71, v15, 4, v4
	v_mov_b32_e32 v4, 0
	v_lshl_add_u64 v[66:67], s[16:17], 0, v[6:7]
	v_mov_b32_e32 v5, v4
	v_mov_b32_e32 v6, v4
	v_mov_b32_e32 v7, v4
	v_mov_b32_e32 v44, v4
	v_mov_b32_e32 v45, v4
	v_mov_b32_e32 v46, v4
	v_mov_b32_e32 v47, v4
	v_mov_b32_e32 v0, v4
	v_mov_b32_e32 v1, v4
	v_mov_b32_e32 v2, v4
	v_mov_b32_e32 v3, v4
	v_mov_b32_e32 v32, v4
	v_mov_b32_e32 v33, v4
	v_mov_b32_e32 v34, v4
	v_mov_b32_e32 v35, v4
	v_mov_b32_e32 v12, v4
	v_mov_b32_e32 v13, v4
	v_mov_b32_e32 v14, v4
	v_mov_b32_e32 v15, v4
	v_mov_b32_e32 v36, v4
	v_mov_b32_e32 v37, v4
	v_mov_b32_e32 v38, v4
	v_mov_b32_e32 v39, v4
	v_mov_b32_e32 v8, v4
	v_mov_b32_e32 v9, v4
	v_mov_b32_e32 v10, v4
	v_mov_b32_e32 v11, v4
	v_mov_b32_e32 v40, v4
	v_mov_b32_e32 v41, v4
	v_mov_b32_e32 v42, v4
	v_mov_b32_e32 v43, v4
	v_mov_b32_e32 v20, v4
	v_mov_b32_e32 v21, v4
	v_mov_b32_e32 v22, v4
	v_mov_b32_e32 v23, v4
	v_mov_b32_e32 v48, v4
	v_mov_b32_e32 v49, v4
	v_mov_b32_e32 v50, v4
	v_mov_b32_e32 v51, v4
	v_mov_b32_e32 v16, v4
	v_mov_b32_e32 v17, v4
	v_mov_b32_e32 v18, v4
	v_mov_b32_e32 v19, v4
	v_mov_b32_e32 v52, v4
	v_mov_b32_e32 v53, v4
	v_mov_b32_e32 v54, v4
	v_mov_b32_e32 v55, v4
	v_mov_b32_e32 v28, v4
	v_mov_b32_e32 v29, v4
	v_mov_b32_e32 v30, v4
	v_mov_b32_e32 v31, v4
	v_mov_b32_e32 v56, v4
	v_mov_b32_e32 v57, v4
	v_mov_b32_e32 v58, v4
	v_mov_b32_e32 v59, v4
	v_mov_b32_e32 v24, v4
	v_mov_b32_e32 v25, v4
	v_mov_b32_e32 v26, v4
	v_mov_b32_e32 v27, v4
	v_mov_b32_e32 v60, v4
	v_mov_b32_e32 v61, v4
	v_mov_b32_e32 v62, v4
	v_mov_b32_e32 v63, v4
; DEV int otid() { int t = threadIdx.x; asm volatile("" : "+v"(t)); return t; }
; template <bool SWAP, class RowA, class Epi>
; DEV void gemm_tile(unsigned char* smem, RowA rowA, const bf16_t* Bt, int K, Epi epi) {
;   const int tid = otid(), lane = tid & 63, wid = tid >> 6, wr = wid >> 1, wc = wid & 1, fr = lane & 15, fq = lane >> 4;
;   const int r0 = tid >> 2;
;   const int a_w = (r0 >> 2) & 3, g_w = (((a_w ^ (a_w >> 1)) & 1) << 1) | (a_w >> 1);
;   const int cc = ((tid & 3) ^ g_w) * 8;
;   const int a_r = (fr >> 2) & 3, g_r = (((a_r ^ (a_r >> 1)) & 1) << 1) | (a_r >> 1);
;   const int rdoff = fr * 64 + ((fq ^ g_r) * 16);
;   const bf16_t* a0 = rowA(r0) + cc;
;   const bf16_t* a1 = rowA(r0 + 64) + cc;
;   const bf16_t* b0 = Bt + (size_t)r0 * K + cc;
;   const bf16_t* b1 = Bt + (size_t)(r0 + 64) * K + cc;
;   f32x4 acc[4][4];
; #pragma unroll
;   for (int m = 0; m < 4; ++m)
; #pragma unroll
;     for (int n = 0; n < 4; ++n) acc[m][n] = f32x4{0.f, 0.f, 0.f, 0.f};
;   const int nk = K / 32;
;   auto stage = [&](int kt, int buf) {
;     unsigned char* SA = smem + buf * 16384 + tid * 16;
;     unsigned char* SB = SA + 8192;
;     const int ko = kt * 32;
;     glds16(a0 + ko, SA); glds16(a1 + ko, SA + 4096);
;     glds16(b0 + ko, SB); glds16(b1 + ko, SB + 4096);
;   };
;   stage(0, 0);
;   for (int t = 0; t < nk; ++t) {
;     asm volatile("s_waitcnt vmcnt(0)" ::: "memory");
;     __syncthreads();
;     if (t + 1 < nk) stage(t + 1, (t + 1) & 1);
;     const unsigned char* SA = smem + (t & 1) * 16384;
;     const unsigned char* SB = SA + 8192;
;     bf16x8 At[4], Bl[4];
; #pragma unroll
;     for (int m = 0; m < 4; ++m) At[m] = *reinterpret_cast<const bf16x8*>(SA + (wr * 64 + m * 16) * 64 + rdoff);
; #pragma unroll
;     for (int n = 0; n < 4; ++n) Bl[n] = *reinterpret_cast<const bf16x8*>(SB + (wc * 64 + n * 16) * 64 + rdoff);
; #pragma unroll
;     for (int m = 0; m < 4; ++m)
; #pragma unroll
;       for (int n = 0; n < 4; ++n)
;         acc[m][n] = SWAP ? __builtin_amdgcn_mfma_f32_16x16x32_bf16(Bl[n], At[m], acc[m][n], 0, 0, 0)
;                          : __builtin_amdgcn_mfma_f32_16x16x32_bf16(At[m], Bl[n], acc[m][n], 0, 0, 0);
;   }
	v_and_b32_e32 v92, 15, v122
	v_bfe_u32 v93, v122, 4, 2
	v_bfe_u32 v94, v122, 1, 3
	v_xor_b32_e32 v93, v93, v94
	v_lshlrev_b32_e32 v93, 4, v93
	v_lshl_or_b32 v71, v92, 7, v93
	v_lshlrev_b32_e32 v80, 1, v80
	v_lshlrev_b32_e32 v81, 1, v81
	v_and_b32_e32 v92, 7, v122
	v_bfe_u32 v93, v122, 4, 3
	v_xor_b32_e32 v92, v92, v93
	v_lshlrev_b32_e32 v92, 4, v92
	v_lshrrev_b32_e32 v93, 3, v122
	v_lshl_or_b32 v92, v93, 11, v92
	v_bfe_u32 v93, v122, 4, 2
	v_lshrrev_b32_e32 v94, 1, v93
	v_xor_b32_e32 v95, v93, v94
	v_and_b32_e32 v95, 1, v95
	v_lshl_or_b32 v94, v95, 1, v94
	v_and_b32_e32 v93, 3, v122
	v_xor_b32_e32 v93, v93, v94
	v_lshlrev_b32_e32 v93, 4, v93
	v_lshrrev_b32_e32 v94, 2, v122
	v_lshl_or_b32 v93, v94, 11, v93
	v_sub_u32_e32 v92, v92, v93
	v_ashrrev_i32_e32 v93, 31, v92
	v_lshl_add_u64 v[68:69], v[68:69], 0, v[92:93]
	s_mov_b32 s8, 0xffc00000
	s_mov_b32 s9, -1
	v_lshl_add_u64 v[68:69], v[68:69], 0, s[8:9]
	v_and_b32_e32 v140, 7, v122
	v_bfe_u32 v141, v122, 4, 3
	v_xor_b32_e32 v140, v140, v141
	v_lshlrev_b32_e32 v140, 4, v140
	v_mov_b32_e32 v143, 0
	v_lshlrev_b32_e32 v142, 11, v128
	v_or_b32_e32 v142, v142, v140
	v_lshl_add_u64 v[144:145], s[46:47], 0, v[142:143]
	v_lshlrev_b32_e32 v142, 11, v129
	v_or_b32_e32 v142, v142, v140
	v_lshl_add_u64 v[146:147], s[46:47], 0, v[142:143]
	v_lshlrev_b32_e32 v142, 11, v130
	v_or_b32_e32 v142, v142, v140
	v_lshl_add_u64 v[148:149], s[46:47], 0, v[142:143]
	v_lshlrev_b32_e32 v142, 11, v131
	v_or_b32_e32 v142, v142, v140
	v_lshl_add_u64 v[150:151], s[46:47], 0, v[142:143]
.LBB0_650:
	s_bitcmp1_b32 s4, 6
	s_cbranch_scc1 .Lpair_odd_650
	s_waitcnt lgkmcnt(0)
	s_barrier
	v_readfirstlane_b32 s8, v70
	s_mov_b32 m0, s8
	v_lshl_add_u64 v[92:93], v[144:145], 0, s[4:5]
	s_mov_b64 s[8:9], 0x10000
	global_load_lds_dwordx4 v[92:93], off
	s_add_i32 m0, m0, 0x1000
	v_lshl_add_u64 v[94:95], v[146:147], 0, s[4:5]
	global_load_lds_dwordx4 v[94:95], off
	s_add_i32 m0, m0, 0x1000
	v_lshl_add_u64 v[92:93], v[148:149], 0, s[4:5]
	global_load_lds_dwordx4 v[92:93], off
	s_add_i32 m0, m0, 0x1000
	v_lshl_add_u64 v[94:95], v[150:151], 0, s[4:5]
	global_load_lds_dwordx4 v[94:95], off
	s_add_i32 m0, m0, 0x1000
	v_lshl_add_u64 v[92:93], v[68:69], 0, s[4:5]
	global_load_lds_dwordx4 v[92:93], off
	s_add_i32 m0, m0, 0x1000
	v_lshl_add_u64 v[94:95], v[92:93], 0, s[8:9]
	global_load_lds_dwordx4 v[94:95], off
	s_add_i32 m0, m0, 0x1000
	v_lshl_add_u64 v[92:93], v[94:95], 0, s[8:9]
	global_load_lds_dwordx4 v[92:93], off
	s_add_i32 m0, m0, 0x1000
	v_lshl_add_u64 v[94:95], v[92:93], 0, s[8:9]
	global_load_lds_dwordx4 v[94:95], off
	s_waitcnt vmcnt(0)
	s_barrier
.Lpair_odd_650:
	s_and_b32 s6, s4, 64
	v_xor_b32_e32 v72, s6, v71
	v_add_u32_e32 v104, v72, v80
	v_add_u32_e32 v72, v72, v81
	ds_read_b128 v[92:95], v104
	ds_read_b128 v[96:99], v104 offset:2048
	ds_read_b128 v[100:103], v104 offset:4096
	ds_read_b128 v[104:107], v104 offset:6144
	ds_read_b128 v[108:111], v72 offset:16384
	ds_read_b128 v[112:115], v72 offset:18432
	ds_read_b128 v[116:119], v72 offset:20480
	ds_read_b128 v[124:127], v72 offset:22528
	s_waitcnt lgkmcnt(0)
	v_mfma_f32_16x16x32_bf16 v[60:63], v[108:111], v[92:95], v[60:63]
	s_add_u32 s4, s4, 64
	s_addc_u32 s5, s5, 0
	s_cmpk_eq_i32 s4, 0x7c0
	v_mfma_f32_16x16x32_bf16 v[24:27], v[112:115], v[92:95], v[24:27]
	v_mfma_f32_16x16x32_bf16 v[56:59], v[116:119], v[92:95], v[56:59]
	v_mfma_f32_16x16x32_bf16 v[28:31], v[124:127], v[92:95], v[28:31]
	v_mfma_f32_16x16x32_bf16 v[52:55], v[108:111], v[96:99], v[52:55]
	v_mfma_f32_16x16x32_bf16 v[16:19], v[112:115], v[96:99], v[16:19]
	v_mfma_f32_16x16x32_bf16 v[48:51], v[116:119], v[96:99], v[48:51]
	v_mfma_f32_16x16x32_bf16 v[20:23], v[124:127], v[96:99], v[20:23]
	v_mfma_f32_16x16x32_bf16 v[40:43], v[108:111], v[100:103], v[40:43]
	v_mfma_f32_16x16x32_bf16 v[8:11], v[112:115], v[100:103], v[8:11]
	v_mfma_f32_16x16x32_bf16 v[36:39], v[116:119], v[100:103], v[36:39]
	v_mfma_f32_16x16x32_bf16 v[12:15], v[124:127], v[100:103], v[12:15]
	v_mfma_f32_16x16x32_bf16 v[32:35], v[108:111], v[104:107], v[32:35]
	v_mfma_f32_16x16x32_bf16 v[0:3], v[112:115], v[104:107], v[0:3]
	v_mfma_f32_16x16x32_bf16 v[44:47], v[116:119], v[104:107], v[44:47]
	v_mfma_f32_16x16x32_bf16 v[4:7], v[124:127], v[104:107], v[4:7]
	s_cbranch_scc0 .LBB0_650
	v_xor_b32_e32 v152, 64, v71
	v_add_u32_e32 v72, v152, v81
	s_waitcnt vmcnt(0)
	s_waitcnt vmcnt(0)
	s_barrier
; DEV unsigned pack2(float a, float b) { return (unsigned)f2bf(a) | ((unsigned)f2bf(b) << 16); }
; DEV float sigmoidf_(float x) { return 1.f / (1.f + __expf(-x)); }
; template <bool SWAP, class RowA, class Epi>
; DEV void gemm_tile(unsigned char* smem, RowA rowA, const bf16_t* Bt, int K, Epi epi) {
;     ...
;     for (int m = 0; m < 4; ++m) At[m] = *reinterpret_cast<const bf16x8*>(SA + (wr * 64 + m * 16) * 64 + rdoff);
; #pragma unroll
;     for (int n = 0; n < 4; ++n) Bl[n] = *reinterpret_cast<const bf16x8*>(SB + (wc * 64 + n * 16) * 64 + rdoff);
; #pragma unroll
;     for (int m = 0; m < 4; ++m)
; #pragma unroll
;       for (int n = 0; n < 4; ++n)
;         acc[m][n] = SWAP ? __builtin_amdgcn_mfma_f32_16x16x32_bf16(Bl[n], At[m], acc[m][n], 0, 0, 0)
;                          : __builtin_amdgcn_mfma_f32_16x16x32_bf16(At[m], Bl[n], acc[m][n], 0, 0, 0);
; DEV void phase_moe1(const Params& p, int l, unsigned char* smem) {
;     ...
; #pragma unroll
;         for (int n = 0; n < 2; ++n) {
;           const int acol = nt * 64 + wc * 32 + n * 16 + fq * 4;
;           const float4 bg4 = *reinterpret_cast<const float4*>(bgu + acol);
;           const float4 bl4 = *reinterpret_cast<const float4*>(bgu + 1024 + acol);
;           const float bgv[4] = {bg4.x, bg4.y, bg4.z, bg4.w}, blv[4] = {bl4.x, bl4.y, bl4.z, bl4.w};
; #pragma unroll
;           for (int m = 0; m < 4; ++m) {
;             const int i = mt * 128 + wr * 64 + m * 16 + fr;
;             if (i < cnt) {
;               float a[4];
; #pragma unroll
;               for (int j = 0; j < 4; ++j) {
;                 float gl = fminf(acc[m][n][j] + bgv[j], 7.f);
;                 float li = fminf(fmaxf(acc[m][n + 2][j] + blv[j], -7.f), 7.f);
;                 a[j] = gl * sigmoidf_(1.702f * gl) * (li + 1.f);
;               }
;               *reinterpret_cast<uint2*>(p.act + (size_t)(rowoff + i) * 1024 + acol) = make_uint2(pack2(a[0], a[1]), pack2(a[2], a[3]));
	ds_read_b128 v[92:95], v72 offset:16384
	ds_read_b128 v[100:103], v72 offset:18432
	ds_read_b128 v[104:107], v72 offset:20480
	ds_read_b128 v[108:111], v72 offset:22528
	v_add_u32_e32 v80, v152, v80
	ds_read_b128 v[96:99], v80
	ds_read_b128 v[112:115], v80 offset:6144
	s_waitcnt lgkmcnt(1)
	v_mfma_f32_16x16x32_bf16 v[64:67], v[92:95], v[96:99], v[60:63]
	v_readlane_b32 s72, v166, 55
	v_readlane_b32 s84, v165, 3
	v_readlane_b32 s85, v165, 4
	v_mfma_f32_16x16x32_bf16 v[24:27], v[100:103], v[96:99], v[24:27]
	s_lshl_b64 s[0:1], s[0:1], 2
	s_mov_b64 s[64:65], s[84:85]
	s_add_u32 s0, s64, s0
	v_mfma_f32_16x16x32_bf16 v[68:71], v[104:107], v[96:99], v[56:59]
	s_addc_u32 s1, s65, s1
	s_lshl_b32 s4, s10, 6
	v_lshl_add_u32 v72, v78, 6, s11
	v_mfma_f32_16x16x32_bf16 v[28:31], v[108:111], v[96:99], v[28:31]
	ds_read_b128 v[96:99], v80 offset:2048
	v_or_b32_e32 v72, v72, v79
	v_add_u32_e32 v78, v72, v77
	s_waitcnt lgkmcnt(0)
	v_mfma_f32_16x16x32_bf16 v[56:59], v[92:95], v[96:99], v[52:55]
	v_ashrrev_i32_e32 v79, 31, v78
	v_readlane_b32 s73, v166, 56
	v_readlane_b32 s74, v166, 57
	v_mfma_f32_16x16x32_bf16 v[16:19], v[100:103], v[96:99], v[16:19]
	v_readlane_b32 s75, v166, 58
	v_readlane_b32 s76, v166, 59
	v_readlane_b32 s77, v166, 60
	v_mfma_f32_16x16x32_bf16 v[60:63], v[104:107], v[96:99], v[48:51]
	v_readlane_b32 s78, v166, 61
	v_readlane_b32 s79, v166, 62
	v_readlane_b32 s80, v166, 63
	v_mfma_f32_16x16x32_bf16 v[20:23], v[108:111], v[96:99], v[20:23]
	ds_read_b128 v[96:99], v80 offset:4096
	v_readlane_b32 s81, v165, 0
	v_readlane_b32 s82, v165, 1
	s_waitcnt lgkmcnt(0)
	v_mfma_f32_16x16x32_bf16 v[48:51], v[92:95], v[96:99], v[40:43]
	v_readlane_b32 s83, v165, 2
	s_nop 1
	v_lshlrev_b32_e32 v40, 5, v74
	v_readlane_b32 s86, v165, 5
	v_mfma_f32_16x16x32_bf16 v[52:55], v[104:107], v[96:99], v[36:39]
	v_readlane_b32 s87, v165, 6
	s_nop 1
	v_lshlrev_b32_e32 v36, 2, v75
	v_or3_b32 v74, v40, s4, v36
	v_ashrrev_i32_e32 v75, 31, v74
	v_lshlrev_b64 v[40:41], 2, v[74:75]
	v_lshl_add_u64 v[80:81], s[0:1], 0, v[40:41]
	s_add_u32 s0, s0, 0x1000
	s_addc_u32 s1, s1, 0
	v_lshl_add_u64 v[40:41], s[0:1], 0, v[40:41]
	global_load_dwordx4 v[36:39], v[80:81], off
	v_mfma_f32_16x16x32_bf16 v[8:11], v[100:103], v[96:99], v[8:11]
	global_load_dwordx4 v[40:43], v[40:41], off
	v_cmp_lt_i32_e64 s[4:5], v72, v76
	v_mfma_f32_16x16x32_bf16 v[12:15], v[108:111], v[96:99], v[12:15]
	v_mfma_f32_16x16x32_bf16 v[32:35], v[92:95], v[112:115], v[32:35]
	v_mfma_f32_16x16x32_bf16 v[0:3], v[100:103], v[112:115], v[0:3]
	v_mfma_f32_16x16x32_bf16 v[44:47], v[104:107], v[112:115], v[44:47]
	v_mfma_f32_16x16x32_bf16 v[4:7], v[108:111], v[112:115], v[4:7]
	s_waitcnt vmcnt(0)
	s_and_saveexec_b64 s[6:7], s[4:5]
	s_cbranch_execz .LBB0_653
	v_add_f32_e32 v64, v64, v36
	v_min_f32_e32 v92, 0x40e00000, v64
	v_add_f32_e32 v64, v68, v40
	v_med3_f32 v94, v64, s2, v89
	v_mul_f32_e32 v64, 0x3fd9db23, v92
	v_mul_f32_e32 v64, 0xbfb8aa3b, v64
	v_exp_f32_e32 v96, v64
	v_add_f32_e32 v64, v65, v37
	v_min_f32_e32 v68, 0x40e00000, v64
	v_mul_f32_e32 v65, 0x3fd9db23, v68
	v_mul_f32_e32 v65, 0xbfb8aa3b, v65
	v_exp_f32_e32 v98, v65
	v_add_f32_e32 v65, v66, v38
	v_min_f32_e32 v93, 0x40e00000, v65
	v_add_f32_e32 v65, v70, v42
	v_med3_f32 v95, v65, s2, v89
	v_mul_f32_e32 v65, 0x3fd9db23, v93
	v_mul_f32_e32 v65, 0xbfb8aa3b, v65
	v_exp_f32_e32 v97, v65
	v_add_f32_e32 v65, v67, v39
	v_add_f32_e32 v64, v69, v41
	v_min_f32_e32 v69, 0x40e00000, v65
	v_add_f32_e32 v65, v71, v43
	v_pk_add_f32 v[70:71], v[96:97], 1.0 op_sel_hi:[1,0]
	v_mul_f32_e32 v66, 0x3fd9db23, v69
	v_div_scale_f32 v96, s[8:9], v71, v71, 1.0
	v_rcp_f32_e32 v97, v96
	v_mul_f32_e32 v66, 0xbfb8aa3b, v66
	v_exp_f32_e32 v99, v66
	v_med3_f32 v64, v64, s2, v89
	v_fma_f32 v100, -v96, v97, 1.0
	v_fmac_f32_e32 v97, v100, v97
	v_div_scale_f32 v100, vcc, 1.0, v71, 1.0
	v_mul_f32_e32 v101, v100, v97
	v_fma_f32 v102, -v96, v101, v100
	v_fmac_f32_e32 v101, v102, v97
	v_fma_f32 v96, -v96, v101, v100
	v_div_fmas_f32 v96, v96, v97, v101
	v_div_fixup_f32 v71, v96, v71, 1.0
	v_div_scale_f32 v96, s[8:9], v70, v70, 1.0
	v_rcp_f32_e32 v97, v96
	v_med3_f32 v65, v65, s2, v89
	v_pk_add_f32 v[64:65], v[64:65], 1.0 op_sel_hi:[1,0]
	v_readlane_b32 s72, v166, 7
	v_fma_f32 v100, -v96, v97, 1.0
	v_fmac_f32_e32 v97, v100, v97
	v_div_scale_f32 v100, vcc, 1.0, v70, 1.0
	v_mul_f32_e32 v101, v100, v97
	v_fma_f32 v102, -v96, v101, v100
	v_fmac_f32_e32 v101, v102, v97
	v_fma_f32 v96, -v96, v101, v100
	v_div_fmas_f32 v96, v96, v97, v101
	v_div_fixup_f32 v70, v96, v70, 1.0
	v_pk_mul_f32 v[70:71], v[92:93], v[70:71]
	v_pk_add_f32 v[92:93], v[94:95], 1.0 op_sel_hi:[1,0]
	v_lshlrev_b64 v[66:67], 11, v[78:79]
	v_pk_mul_f32 v[70:71], v[92:93], v[70:71]
	v_pk_add_f32 v[92:93], v[98:99], 1.0 op_sel_hi:[1,0]
	v_readlane_b32 s80, v166, 15
	v_div_scale_f32 v94, s[8:9], v93, v93, 1.0
	v_rcp_f32_e32 v95, v94
	v_readlane_b32 s81, v166, 16
	v_readlane_b32 s73, v166, 8
	v_readlane_b32 s74, v166, 9
	v_fma_f32 v96, -v94, v95, 1.0
	v_fmac_f32_e32 v95, v96, v95
	v_div_scale_f32 v96, vcc, 1.0, v93, 1.0
	v_mul_f32_e32 v97, v96, v95
	v_fma_f32 v98, -v94, v97, v96
	v_fmac_f32_e32 v97, v98, v95
	v_fma_f32 v94, -v94, v97, v96
	v_div_fmas_f32 v94, v94, v95, v97
	v_div_fixup_f32 v93, v94, v93, 1.0
	v_div_scale_f32 v94, s[8:9], v92, v92, 1.0
	v_rcp_f32_e32 v95, v94
	v_lshl_add_u64 v[66:67], s[80:81], 0, v[66:67]
	v_lshl_add_u64 v[66:67], v[74:75], 1, v[66:67]
	v_readlane_b32 s75, v166, 10
	v_fma_f32 v96, -v94, v95, 1.0
	v_fmac_f32_e32 v95, v96, v95
	v_div_scale_f32 v96, vcc, 1.0, v92, 1.0
	v_mul_f32_e32 v97, v96, v95
	v_fma_f32 v98, -v94, v97, v96
	v_fmac_f32_e32 v97, v98, v95
	v_fma_f32 v94, -v94, v97, v96
	v_div_fmas_f32 v94, v94, v95, v97
	v_div_fixup_f32 v92, v94, v92, 1.0
	v_pk_mul_f32 v[68:69], v[68:69], v[92:93]
	v_readlane_b32 s76, v166, 11
	v_pk_mul_f32 v[64:65], v[64:65], v[68:69]
	v_and_b32_sdwa v68, v71, v90 dst_sel:DWORD dst_unused:UNUSED_PAD src0_sel:WORD_1 src1_sel:DWORD
	v_and_b32_sdwa v69, v70, v90 dst_sel:DWORD dst_unused:UNUSED_PAD src0_sel:WORD_1 src1_sel:DWORD
	v_add3_u32 v69, v70, v69, s3
	v_add3_u32 v68, v71, v68, s3
	v_and_b32_sdwa v70, v65, v90 dst_sel:DWORD dst_unused:UNUSED_PAD src0_sel:WORD_1 src1_sel:DWORD
	v_and_b32_sdwa v71, v64, v90 dst_sel:DWORD dst_unused:UNUSED_PAD src0_sel:WORD_1 src1_sel:DWORD
	v_add3_u32 v65, v65, v70, s3
	v_add3_u32 v64, v64, v71, s3
	v_and_b32_e32 v65, 0xffff0000, v65
	v_and_b32_e32 v64, 0xffff0000, v64
	v_or_b32_sdwa v65, v65, v68 dst_sel:DWORD dst_unused:UNUSED_PAD src0_sel:DWORD src1_sel:WORD_1
	v_or_b32_sdwa v64, v64, v69 dst_sel:DWORD dst_unused:UNUSED_PAD src0_sel:DWORD src1_sel:WORD_1
	v_readlane_b32 s77, v166, 12
	v_readlane_b32 s78, v166, 13
	v_readlane_b32 s79, v166, 14
	v_readlane_b32 s82, v166, 17
	v_readlane_b32 s83, v166, 18
	v_readlane_b32 s84, v166, 19
	v_readlane_b32 s85, v166, 20
	v_readlane_b32 s86, v166, 21
	v_readlane_b32 s87, v166, 22
	global_store_dwordx2 v[66:67], v[64:65], off

; DEV int otid() { int t = threadIdx.x; asm volatile("" : "+v"(t)); return t; }
; template <bool SWAP, class RowA, class Epi>
; DEV void gemm_tile(unsigned char* smem, RowA rowA, const bf16_t* Bt, int K, Epi epi) {
;   const int tid = otid(), lane = tid & 63, wid = tid >> 6, wr = wid >> 1, wc = wid & 1, fr = lane & 15, fq = lane >> 4;
;   const int r0 = tid >> 2;
;   const int a_w = (r0 >> 2) & 3, g_w = (((a_w ^ (a_w >> 1)) & 1) << 1) | (a_w >> 1);
;   const int cc = ((tid & 3) ^ g_w) * 8;
;   const int a_r = (fr >> 2) & 3, g_r = (((a_r ^ (a_r >> 1)) & 1) << 1) | (a_r >> 1);
;   const int rdoff = fr * 64 + ((fq ^ g_r) * 16);
;   const bf16_t* a0 = rowA(r0) + cc;
;   const bf16_t* a1 = rowA(r0 + 64) + cc;
;   const bf16_t* b0 = Bt + (size_t)r0 * K + cc;
;   const bf16_t* b1 = Bt + (size_t)(r0 + 64) * K + cc;
; DEV void phase_moe1(const Params& p, int l, unsigned char* smem) {
;     ...
;   for (int t = blockIdx.x; t < ntile; t += gridDim.x) {
;     int e = 0;
;     while (s_tile[e + 1] <= t) ++e;
;     const int local = t - s_tile[e], cnt = s_cnt[e], nmt = (cnt + 127) >> 7;
;     const int mt = local / NTN_, nt = local % NTN_;
;     const int* lst = p.list + e * NTOK;
;     const int rowoff = s_off[e];
;     const float* bgu = p.b_gu + (size_t)(l * 32 + e) * 2048;
;     gemm_tile<true>(smem, [&](int r) { int i = min(mt * 128 + r, cnt - 1); return p.hbuf + (size_t)lst[i] * 1024; },
;       p.wgu_t + ((size_t)(l * 32 + e) * 2048 + nt * 128) * 1024, 1024,
.LBB0_2340:
	v_mov_b32_e32 v0, s1
	ds_read_b32 v0, v0 offset:33032
	s_add_i32 s0, s0, 1
	s_add_i32 s1, s1, 4
	s_add_u32 s4, s4, 0x400000
	s_addc_u32 s5, s5, 0
	s_waitcnt lgkmcnt(0)
	v_cmp_ge_i32_e32 vcc, s23, v0
	s_cbranch_vccnz .LBB0_2340
	v_mov_b32_e32 v0, s1
	ds_read_b32 v1, v0 offset:33024
	v_readlane_b32 s48, v165, 39
	s_mul_i32 s16, s0, 0x4200
	v_readlane_b32 s52, v165, 43
	v_readlane_b32 s53, v165, 44
	s_waitcnt lgkmcnt(0)
	v_readfirstlane_b32 s1, v1
	s_sub_i32 s1, s23, s1
	s_ashr_i32 s8, s1, 31
	s_lshr_b32 s8, s8, 28
	s_add_i32 s11, s1, s8
	s_and_b32 s8, s11, -16
	v_readlane_b32 s54, v165, 45
	v_readlane_b32 s55, v165, 46
	v_readlane_b32 s60, v165, 51
	v_readlane_b32 s61, v165, 52
	s_lshl_b64 s[6:7], s[16:17], 2
	s_sub_i32 s10, s1, s8
	v_readlane_b32 s62, v165, 53
	v_readlane_b32 s63, v165, 54
	s_mov_b64 s[52:53], s[60:61]
	s_add_u32 s12, s52, s6
	s_addc_u32 s13, s53, s7
	s_add_i32 s16, s0, 32
	s_lshl_b32 s6, s10, 7
	s_lshl_b64 s[0:1], s[16:17], 11
	s_ashr_i32 s7, s6, 31
	v_add_u32_e32 v0, 0x8000, v0
	s_add_u32 s8, s0, s6
	ds_read2_b32 v[74:75], v0 offset1:32
	s_addc_u32 s9, s1, s7
	s_lshl_b64 s[8:9], s[8:9], 11
	s_add_u32 s8, s36, s8
	s_addc_u32 s9, s37, s9
	v_mov_b32_e32 v14, v122
	s_lshl_b32 s11, s11, 3
	s_and_b32 s11, s11, 0xffffff80
	v_ashrrev_i32_e32 v0, 2, v14
	v_add_u32_e32 v1, s11, v0
	s_waitcnt lgkmcnt(0)
	v_add_u32_e32 v5, -1, v74
	v_add_u32_e32 v4, 64, v0
	v_min_i32_e32 v2, v1, v5
	v_add_u32_e32 v1, s11, v4
	v_min_i32_e32 v6, v1, v5
	v_ashrrev_i32_e32 v3, 31, v2
	v_ashrrev_i32_e32 v7, 31, v6
	v_lshl_add_u64 v[2:3], v[2:3], 2, s[12:13]
	v_lshl_add_u64 v[6:7], v[6:7], 2, s[12:13]
	global_load_dword v2, v[2:3], off
	s_nop 0
	global_load_dword v6, v[6:7], off
	v_lshrrev_b32_e32 v132, 3, v122
	v_add_u32_e32 v132, s11, v132
	v_min_i32_e32 v134, v132, v5
	v_ashrrev_i32_e32 v135, 31, v134
	v_lshl_add_u64 v[134:135], v[134:135], 2, s[12:13]
	global_load_dword v128, v[134:135], off
	v_add_u32_e32 v136, 32, v132
	v_min_i32_e32 v134, v136, v5
	v_ashrrev_i32_e32 v135, 31, v134
	v_lshl_add_u64 v[134:135], v[134:135], 2, s[12:13]
	global_load_dword v129, v[134:135], off
	v_add_u32_e32 v136, 64, v132
	v_min_i32_e32 v134, v136, v5
	v_ashrrev_i32_e32 v135, 31, v134
	v_lshl_add_u64 v[134:135], v[134:135], 2, s[12:13]
	global_load_dword v130, v[134:135], off
	v_add_u32_e32 v136, 96, v132
	v_min_i32_e32 v134, v136, v5
	v_ashrrev_i32_e32 v135, 31, v134
	v_lshl_add_u64 v[134:135], v[134:135], 2, s[12:13]
	global_load_dword v131, v[134:135], off
	v_lshrrev_b32_e32 v1, 4, v14
	v_lshrrev_b32_e32 v3, 5, v14
	v_xor_b32_e32 v3, v1, v3
	v_lshlrev_b32_e32 v3, 1, v3
	v_bfe_u32 v7, v14, 5, 1
	v_and_b32_e32 v8, 3, v14
	v_and_b32_e32 v3, 2, v3
	v_lshrrev_b32_e32 v5, 2, v14
	v_lshrrev_b32_e32 v9, 3, v14
	v_bitop3_b32 v3, v3, v8, v7 bitop3:0x36
	v_lshlrev_b32_e32 v70, 4, v14
	v_xor_b32_e32 v5, v5, v9
	v_lshlrev_b32_e32 v72, 4, v3
	v_add_u32_e32 v9, 0x2000, v70
	v_add_u32_e32 v12, 0x3000, v70
	v_lshlrev_b32_e32 v13, 1, v5
	v_bfe_u32 v77, v14, 4, 2
	v_bfe_u32 v10, v14, 3, 1
	v_ashrrev_i32_e32 v1, 31, v0
	v_readfirstlane_b32 s12, v70
	v_add_u32_e32 v11, 0x1000, v70
	v_readfirstlane_b32 s16, v9
	v_readfirstlane_b32 s24, v12
	v_and_b32_e32 v9, 2, v13
	v_lshlrev_b64 v[0:1], 11, v[0:1]
	v_ashrrev_i32_e32 v5, 31, v4
	v_readfirstlane_b32 s13, v11
	v_bitop3_b32 v15, v9, v77, v10 bitop3:0x36
	s_mov_b32 m0, s12
	v_lshlrev_b64 v[4:5], 11, v[4:5]
	v_lshl_add_u64 v[8:9], s[8:9], 0, v[0:1]
	v_lshl_add_u64 v[4:5], s[8:9], 0, v[4:5]
	v_lshl_add_u64 v[8:9], v[8:9], 0, v[72:73]
	v_lshl_add_u64 v[4:5], v[4:5], 0, v[72:73]
	v_and_b32_e32 v79, 15, v14
	s_lshl_b64 s[6:7], s[6:7], 11
	v_lshl_add_u64 v[0:1], v[0:1], 0, s[6:7]
	v_bfe_u32 v76, v14, 6, 1
	v_ashrrev_i32_e32 v78, 7, v14
	v_or_b32_e32 v0, v0, v72
	v_lshlrev_b32_e32 v80, 12, v78
	v_lshlrev_b32_e32 v81, 12, v76
	v_lshl_add_u64 v[68:69], s[4:5], 0, v[0:1]
	s_mov_b32 s6, 0
	s_mov_b64 s[4:5], 0
	v_readlane_b32 s49, v165, 40
	v_readlane_b32 s50, v165, 41
	v_readlane_b32 s51, v165, 42
	v_readlane_b32 s56, v165, 47
	v_readlane_b32 s57, v165, 48
	v_readlane_b32 s58, v165, 49
	v_readlane_b32 s59, v165, 50
	s_mov_b64 s[54:55], s[62:63]
	s_waitcnt vmcnt(1)
; DEV int otid() { int t = threadIdx.x; asm volatile("" : "+v"(t)); return t; }
; template <bool SWAP, class RowA, class Epi>
; DEV void gemm_tile(unsigned char* smem, RowA rowA, const bf16_t* Bt, int K, Epi epi) {
;   const int tid = otid(), lane = tid & 63, wid = tid >> 6, wr = wid >> 1, wc = wid & 1, fr = lane & 15, fq = lane >> 4;
;   const int r0 = tid >> 2;
;   const int a_w = (r0 >> 2) & 3, g_w = (((a_w ^ (a_w >> 1)) & 1) << 1) | (a_w >> 1);
;   const int cc = ((tid & 3) ^ g_w) * 8;
;   const int a_r = (fr >> 2) & 3, g_r = (((a_r ^ (a_r >> 1)) & 1) << 1) | (a_r >> 1);
;   const int rdoff = fr * 64 + ((fq ^ g_r) * 16);
;   const bf16_t* a0 = rowA(r0) + cc;
;   const bf16_t* a1 = rowA(r0 + 64) + cc;
;   const bf16_t* b0 = Bt + (size_t)r0 * K + cc;
;   const bf16_t* b1 = Bt + (size_t)(r0 + 64) * K + cc;
;   f32x4 acc[4][4];
; #pragma unroll
;   for (int m = 0; m < 4; ++m)
; #pragma unroll
;     for (int n = 0; n < 4; ++n) acc[m][n] = f32x4{0.f, 0.f, 0.f, 0.f};
;   const int nk = K / 32;
;   auto stage = [&](int kt, int buf) {
;     unsigned char* SA = smem + buf * 16384 + tid * 16;
;     unsigned char* SB = SA + 8192;
;     const int ko = kt * 32;
;     glds16(a0 + ko, SA); glds16(a1 + ko, SA + 4096);
;     glds16(b0 + ko, SB); glds16(b1 + ko, SB + 4096);
;   };
;   stage(0, 0);
	v_ashrrev_i32_e32 v3, 31, v2
	s_waitcnt vmcnt(0)
	v_ashrrev_i32_e32 v7, 31, v6
	v_lshlrev_b64 v[2:3], 11, v[2:3]
	v_lshlrev_b64 v[6:7], 11, v[6:7]
	v_lshl_add_u64 v[12:13], s[46:47], 0, v[2:3]
	v_lshl_add_u64 v[10:11], s[46:47], 0, v[6:7]
	v_lshl_add_u64 v[12:13], v[12:13], 0, v[72:73]
	v_lshl_add_u64 v[10:11], v[10:11], 0, v[72:73]
	s_mov_b32 m0, s13
	v_or_b32_e32 v2, v2, v72
	s_mov_b32 m0, s16
	v_or_b32_e32 v6, v6, v72
	s_mov_b32 m0, s24
	v_lshl_add_u64 v[64:65], s[14:15], 0, v[2:3]
	v_lshlrev_b32_e32 v4, 6, v79
	v_lshl_or_b32 v71, v15, 4, v4
	v_mov_b32_e32 v4, 0
	v_lshl_add_u64 v[66:67], s[14:15], 0, v[6:7]
	v_mov_b32_e32 v5, v4
	v_mov_b32_e32 v6, v4
	v_mov_b32_e32 v7, v4
	v_mov_b32_e32 v40, v4
	v_mov_b32_e32 v41, v4
	v_mov_b32_e32 v42, v4
	v_mov_b32_e32 v43, v4
	v_mov_b32_e32 v0, v4
	v_mov_b32_e32 v1, v4
	v_mov_b32_e32 v2, v4
	v_mov_b32_e32 v3, v4
	v_mov_b32_e32 v32, v4
	v_mov_b32_e32 v33, v4
	v_mov_b32_e32 v34, v4
	v_mov_b32_e32 v35, v4
	v_mov_b32_e32 v12, v4
	v_mov_b32_e32 v13, v4
	v_mov_b32_e32 v14, v4
	v_mov_b32_e32 v15, v4
	v_mov_b32_e32 v36, v4
	v_mov_b32_e32 v37, v4
	v_mov_b32_e32 v38, v4
	v_mov_b32_e32 v39, v4
	v_mov_b32_e32 v8, v4
	v_mov_b32_e32 v9, v4
	v_mov_b32_e32 v10, v4
	v_mov_b32_e32 v11, v4
	v_mov_b32_e32 v44, v4
	v_mov_b32_e32 v45, v4
	v_mov_b32_e32 v46, v4
	v_mov_b32_e32 v47, v4
	v_mov_b32_e32 v20, v4
	v_mov_b32_e32 v21, v4
	v_mov_b32_e32 v22, v4
	v_mov_b32_e32 v23, v4
	v_mov_b32_e32 v48, v4
	v_mov_b32_e32 v49, v4
	v_mov_b32_e32 v50, v4
	v_mov_b32_e32 v51, v4
	v_mov_b32_e32 v16, v4
	v_mov_b32_e32 v17, v4
	v_mov_b32_e32 v18, v4
	v_mov_b32_e32 v19, v4
	v_mov_b32_e32 v52, v4
	v_mov_b32_e32 v53, v4
	v_mov_b32_e32 v54, v4
	v_mov_b32_e32 v55, v4
	v_mov_b32_e32 v28, v4
	v_mov_b32_e32 v29, v4
	v_mov_b32_e32 v30, v4
	v_mov_b32_e32 v31, v4
	v_mov_b32_e32 v56, v4
	v_mov_b32_e32 v57, v4
	v_mov_b32_e32 v58, v4
	v_mov_b32_e32 v59, v4
	v_mov_b32_e32 v24, v4
	v_mov_b32_e32 v25, v4
	v_mov_b32_e32 v26, v4
	v_mov_b32_e32 v27, v4
	v_mov_b32_e32 v60, v4
	v_mov_b32_e32 v61, v4
	v_mov_b32_e32 v62, v4
	v_mov_b32_e32 v63, v4
	v_and_b32_e32 v92, 15, v122
	v_bfe_u32 v93, v122, 4, 2
	v_bfe_u32 v94, v122, 1, 3
	v_xor_b32_e32 v93, v93, v94
	v_lshlrev_b32_e32 v93, 4, v93
	v_lshl_or_b32 v71, v92, 7, v93
	v_lshlrev_b32_e32 v80, 1, v80
	v_lshlrev_b32_e32 v81, 1, v81
	v_and_b32_e32 v92, 7, v122
	v_bfe_u32 v93, v122, 4, 3
	v_xor_b32_e32 v92, v92, v93
	v_lshlrev_b32_e32 v92, 4, v92
	v_lshrrev_b32_e32 v93, 3, v122
	v_lshl_or_b32 v92, v93, 11, v92
	v_bfe_u32 v93, v122, 4, 2
	v_lshrrev_b32_e32 v94, 1, v93
	v_xor_b32_e32 v95, v93, v94
	v_and_b32_e32 v95, 1, v95
	v_lshl_or_b32 v94, v95, 1, v94
	v_and_b32_e32 v93, 3, v122
	v_xor_b32_e32 v93, v93, v94
	v_lshlrev_b32_e32 v93, 4, v93
	v_lshrrev_b32_e32 v94, 2, v122
	v_lshl_or_b32 v93, v94, 11, v93
	v_sub_u32_e32 v92, v92, v93
	v_ashrrev_i32_e32 v93, 31, v92
	v_lshl_add_u64 v[68:69], v[68:69], 0, v[92:93]
	s_mov_b32 s8, 0x7c00000
	s_mov_b32 s9, 0
	v_lshl_add_u64 v[68:69], v[68:69], 0, s[8:9]
	v_and_b32_e32 v140, 7, v122
	v_bfe_u32 v141, v122, 4, 3
	v_xor_b32_e32 v140, v140, v141
	v_lshlrev_b32_e32 v140, 4, v140
	v_mov_b32_e32 v143, 0
	v_lshlrev_b32_e32 v142, 11, v128
	v_or_b32_e32 v142, v142, v140
	v_lshl_add_u64 v[144:145], s[46:47], 0, v[142:143]
	v_lshlrev_b32_e32 v142, 11, v129
	v_or_b32_e32 v142, v142, v140
	v_lshl_add_u64 v[146:147], s[46:47], 0, v[142:143]
	v_lshlrev_b32_e32 v142, 11, v130
	v_or_b32_e32 v142, v142, v140
	v_lshl_add_u64 v[148:149], s[46:47], 0, v[142:143]
	v_lshlrev_b32_e32 v142, 11, v131
	v_or_b32_e32 v142, v142, v140
	v_lshl_add_u64 v[150:151], s[46:47], 0, v[142:143]

; template <bool SWAP, class RowA, class Epi>
; DEV void gemm_tile(unsigned char* smem, RowA rowA, const bf16_t* Bt, int K, Epi epi) {
;     ...
;   for (int t = 0; t < nk; ++t) {
;     asm volatile("s_waitcnt vmcnt(0)" ::: "memory");
;     __syncthreads();
;     if (t + 1 < nk) stage(t + 1, (t + 1) & 1);
;     const unsigned char* SA = smem + (t & 1) * 16384;
;     const unsigned char* SB = SA + 8192;
;     bf16x8 At[4], Bl[4];
; #pragma unroll
;     for (int m = 0; m < 4; ++m) At[m] = *reinterpret_cast<const bf16x8*>(SA + (wr * 64 + m * 16) * 64 + rdoff);
; #pragma unroll
;     for (int n = 0; n < 4; ++n) Bl[n] = *reinterpret_cast<const bf16x8*>(SB + (wc * 64 + n * 16) * 64 + rdoff);
; #pragma unroll
;     for (int m = 0; m < 4; ++m)
; #pragma unroll
;       for (int n = 0; n < 4; ++n)
;         acc[m][n] = SWAP ? __builtin_amdgcn_mfma_f32_16x16x32_bf16(Bl[n], At[m], acc[m][n], 0, 0, 0)
;                          : __builtin_amdgcn_mfma_f32_16x16x32_bf16(At[m], Bl[n], acc[m][n], 0, 0, 0);
; DEV void phase_moe1(const Params& p, int l, unsigned char* smem) {
;     ...
; #pragma unroll
;         for (int n = 0; n < 2; ++n) {
;           const int acol = nt * 64 + wc * 32 + n * 16 + fq * 4;
;           const float4 bg4 = *reinterpret_cast<const float4*>(bgu + acol);
;           const float4 bl4 = *reinterpret_cast<const float4*>(bgu + 1024 + acol);
;           const float bgv[4] = {bg4.x, bg4.y, bg4.z, bg4.w}, blv[4] = {bl4.x, bl4.y, bl4.z, bl4.w};
; #pragma unroll
;           for (int m = 0; m < 4; ++m) {
;             const int i = mt * 128 + wr * 64 + m * 16 + fr;
;             if (i < cnt) {
.Lpair_odd_2342:
	s_and_b32 s6, s4, 64
	v_xor_b32_e32 v72, s6, v71
	v_add_u32_e32 v116, v72, v80
	v_add_u32_e32 v72, v72, v81
	ds_read_b128 v[92:95], v72 offset:16384
	ds_read_b128 v[96:99], v72 offset:18432
	ds_read_b128 v[100:103], v116
	ds_read_b128 v[104:107], v116 offset:2048
	ds_read_b128 v[108:111], v72 offset:20480
	ds_read_b128 v[112:115], v72 offset:22528
	s_waitcnt lgkmcnt(0)
	v_mfma_f32_16x16x32_bf16 v[60:63], v[92:95], v[100:103], v[60:63]
	s_add_u32 s4, s4, 64
	s_addc_u32 s5, s5, 0
	s_cmpk_eq_i32 s4, 0x7c0
	v_mfma_f32_16x16x32_bf16 v[24:27], v[96:99], v[100:103], v[24:27]
	v_mfma_f32_16x16x32_bf16 v[56:59], v[108:111], v[100:103], v[56:59]
	v_mfma_f32_16x16x32_bf16 v[28:31], v[112:115], v[100:103], v[28:31]
	v_mfma_f32_16x16x32_bf16 v[52:55], v[92:95], v[104:107], v[52:55]
	v_mfma_f32_16x16x32_bf16 v[16:19], v[96:99], v[104:107], v[16:19]
	v_mfma_f32_16x16x32_bf16 v[48:51], v[108:111], v[104:107], v[48:51]
	v_mfma_f32_16x16x32_bf16 v[20:23], v[112:115], v[104:107], v[20:23]
	ds_read_b128 v[100:103], v116 offset:4096
	ds_read_b128 v[104:107], v116 offset:6144
	s_waitcnt lgkmcnt(0)
	v_mfma_f32_16x16x32_bf16 v[44:47], v[92:95], v[100:103], v[44:47]
	v_mfma_f32_16x16x32_bf16 v[8:11], v[96:99], v[100:103], v[8:11]
	v_mfma_f32_16x16x32_bf16 v[36:39], v[108:111], v[100:103], v[36:39]
	v_mfma_f32_16x16x32_bf16 v[12:15], v[112:115], v[100:103], v[12:15]
	v_mfma_f32_16x16x32_bf16 v[32:35], v[92:95], v[104:107], v[32:35]
	v_mfma_f32_16x16x32_bf16 v[0:3], v[96:99], v[104:107], v[0:3]
	v_mfma_f32_16x16x32_bf16 v[40:43], v[108:111], v[104:107], v[40:43]
	v_mfma_f32_16x16x32_bf16 v[4:7], v[112:115], v[104:107], v[4:7]
	s_cbranch_scc0 .LBB0_2342
	v_xor_b32_e32 v152, 64, v71
	v_add_u32_e32 v72, v152, v81
	s_waitcnt vmcnt(0)
	s_waitcnt vmcnt(0)
	s_barrier
	ds_read_b128 v[92:95], v72 offset:16384
	ds_read_b128 v[100:103], v72 offset:18432
	ds_read_b128 v[104:107], v72 offset:20480
	ds_read_b128 v[108:111], v72 offset:22528
	v_add_u32_e32 v80, v152, v80
	ds_read_b128 v[96:99], v80
	ds_read_b128 v[112:115], v80 offset:6144
	s_waitcnt lgkmcnt(1)
	v_mfma_f32_16x16x32_bf16 v[64:67], v[92:95], v[96:99], v[60:63]
	v_readlane_b32 s48, v166, 55
	v_readlane_b32 s60, v165, 3
	v_readlane_b32 s61, v165, 4
	v_mfma_f32_16x16x32_bf16 v[24:27], v[100:103], v[96:99], v[24:27]
	s_lshl_b64 s[0:1], s[0:1], 2
	s_mov_b64 s[12:13], s[60:61]
	s_add_u32 s0, s12, s0
	v_mfma_f32_16x16x32_bf16 v[68:71], v[104:107], v[96:99], v[56:59]
	s_addc_u32 s1, s13, s1
	s_lshl_b32 s4, s10, 6
	v_lshl_add_u32 v72, v78, 6, s11
	v_mfma_f32_16x16x32_bf16 v[28:31], v[108:111], v[96:99], v[28:31]
	ds_read_b128 v[96:99], v80 offset:2048
	v_or_b32_e32 v72, v72, v79
	v_add_u32_e32 v78, v72, v75
	s_waitcnt lgkmcnt(0)
	v_mfma_f32_16x16x32_bf16 v[56:59], v[92:95], v[96:99], v[52:55]
	v_cmp_lt_i32_e64 s[6:7], v72, v74
	v_ashrrev_i32_e32 v79, 31, v78
	v_readlane_b32 s49, v166, 56
	v_mfma_f32_16x16x32_bf16 v[16:19], v[100:103], v[96:99], v[16:19]
	v_readlane_b32 s50, v166, 57
	v_readlane_b32 s51, v166, 58
	v_readlane_b32 s52, v166, 59
	v_mfma_f32_16x16x32_bf16 v[60:63], v[104:107], v[96:99], v[48:51]
	v_readlane_b32 s53, v166, 60
	v_readlane_b32 s54, v166, 61
	v_readlane_b32 s55, v166, 62
	v_mfma_f32_16x16x32_bf16 v[20:23], v[108:111], v[96:99], v[20:23]
	ds_read_b128 v[96:99], v80 offset:4096
	v_readlane_b32 s56, v166, 63
	v_readlane_b32 s57, v165, 0
	s_waitcnt lgkmcnt(0)
	v_mfma_f32_16x16x32_bf16 v[48:51], v[92:95], v[96:99], v[44:47]
	v_readlane_b32 s58, v165, 1
	s_nop 1
	v_lshlrev_b32_e32 v44, 5, v76
	v_readlane_b32 s59, v165, 2
	v_mfma_f32_16x16x32_bf16 v[52:55], v[104:107], v[96:99], v[36:39]
	v_readlane_b32 s62, v165, 5
	v_readlane_b32 s63, v165, 6
	s_nop 0
	v_lshlrev_b32_e32 v36, 2, v77
	v_or3_b32 v76, v44, s4, v36
	v_ashrrev_i32_e32 v77, 31, v76
	v_lshlrev_b64 v[44:45], 2, v[76:77]
	v_lshl_add_u64 v[80:81], s[0:1], 0, v[44:45]
	s_add_u32 s0, s0, 0x1000
	s_addc_u32 s1, s1, 0
	v_lshl_add_u64 v[44:45], s[0:1], 0, v[44:45]
	global_load_dwordx4 v[36:39], v[80:81], off
	v_mfma_f32_16x16x32_bf16 v[8:11], v[100:103], v[96:99], v[8:11]
	global_load_dwordx4 v[44:47], v[44:45], off
	v_mfma_f32_16x16x32_bf16 v[12:15], v[108:111], v[96:99], v[12:15]
	v_mfma_f32_16x16x32_bf16 v[32:35], v[92:95], v[112:115], v[32:35]
	v_mfma_f32_16x16x32_bf16 v[0:3], v[100:103], v[112:115], v[0:3]
	v_mfma_f32_16x16x32_bf16 v[40:43], v[104:107], v[112:115], v[40:43]
	v_mfma_f32_16x16x32_bf16 v[4:7], v[108:111], v[112:115], v[4:7]
	s_waitcnt vmcnt(0)
	s_and_saveexec_b64 s[4:5], s[6:7]
	s_cbranch_execz .LBB0_2345
; DEV unsigned pack2(float a, float b) { return (unsigned)f2bf(a) | ((unsigned)f2bf(b) << 16); }
; DEV float sigmoidf_(float x) { return 1.f / (1.f + __expf(-x)); }
; DEV void phase_moe1(const Params& p, int l, unsigned char* smem) {
;     ...
;               float a[4];
; #pragma unroll
;               for (int j = 0; j < 4; ++j) {
;                 float gl = fminf(acc[m][n][j] + bgv[j], 7.f);
;                 float li = fminf(fmaxf(acc[m][n + 2][j] + blv[j], -7.f), 7.f);
;                 a[j] = gl * sigmoidf_(1.702f * gl) * (li + 1.f);
;               }
;               *reinterpret_cast<uint2*>(p.act + (size_t)(rowoff + i) * 1024 + acol) = make_uint2(pack2(a[0], a[1]), pack2(a[2], a[3]));
	v_add_f32_e32 v65, v65, v37
	v_min_f32_e32 v94, 0x40e00000, v65
	v_add_f32_e32 v65, v69, v45
	v_med3_f32 v96, v65, s2, v89
	v_mul_f32_e32 v65, 0x3fd9db23, v94
	v_mul_f32_e32 v65, 0xbfb8aa3b, v65
	v_add_f32_e32 v64, v64, v36
	v_exp_f32_e32 v98, v65
	v_add_f32_e32 v65, v66, v38
	v_min_f32_e32 v64, 0x40e00000, v64
	v_min_f32_e32 v65, 0x40e00000, v65
	v_add_f32_e32 v66, v70, v46
	v_mul_f32_e32 v92, 0x3fd9db23, v64
	v_med3_f32 v69, v66, s2, v89
	v_mul_f32_e32 v66, 0x3fd9db23, v65
	v_mul_f32_e32 v92, 0xbfb8aa3b, v92
	v_mul_f32_e32 v66, 0xbfb8aa3b, v66
	v_exp_f32_e32 v92, v92
	v_exp_f32_e32 v93, v66
	v_add_f32_e32 v66, v67, v39
	v_min_f32_e32 v95, 0x40e00000, v66
	v_add_f32_e32 v66, v71, v47
	v_med3_f32 v97, v66, s2, v89
	v_mul_f32_e32 v66, 0x3fd9db23, v95
	v_mul_f32_e32 v66, 0xbfb8aa3b, v66
	v_exp_f32_e32 v99, v66
	v_pk_add_f32 v[66:67], v[92:93], 1.0 op_sel_hi:[1,0]
	v_add_f32_e32 v68, v68, v44
	v_div_scale_f32 v92, s[8:9], v67, v67, 1.0
	v_rcp_f32_e32 v93, v92
	v_med3_f32 v68, v68, s2, v89
	v_lshlrev_b64 v[70:71], 11, v[78:79]
	v_lshl_add_u64 v[70:71], s[80:81], 0, v[70:71]
	v_fma_f32 v100, -v92, v93, 1.0
	v_fmac_f32_e32 v93, v100, v93
	v_div_scale_f32 v100, vcc, 1.0, v67, 1.0
	v_mul_f32_e32 v101, v100, v93
	v_fma_f32 v102, -v92, v101, v100
	v_fmac_f32_e32 v101, v102, v93
	v_fma_f32 v92, -v92, v101, v100
	v_div_scale_f32 v100, s[8:9], v66, v66, 1.0
	v_rcp_f32_e32 v102, v100
	v_div_fmas_f32 v92, v92, v93, v101
	v_div_fixup_f32 v67, v92, v67, 1.0
	v_lshl_add_u64 v[70:71], v[76:77], 1, v[70:71]
	v_fma_f32 v92, -v100, v102, 1.0
	v_fmac_f32_e32 v102, v92, v102
	v_div_scale_f32 v92, vcc, 1.0, v66, 1.0
	v_mul_f32_e32 v93, v92, v102
	v_fma_f32 v101, -v100, v93, v92
	v_fmac_f32_e32 v93, v101, v102
	v_fma_f32 v92, -v100, v93, v92
	v_div_fmas_f32 v92, v92, v102, v93
	v_div_fixup_f32 v66, v92, v66, 1.0
	v_pk_add_f32 v[92:93], v[98:99], 1.0 op_sel_hi:[1,0]
	v_pk_mul_f32 v[64:65], v[64:65], v[66:67]
	v_div_scale_f32 v98, s[8:9], v93, v93, 1.0
	v_rcp_f32_e32 v99, v98
	v_pk_add_f32 v[66:67], v[68:69], 1.0 op_sel_hi:[1,0]
	s_nop 0
	v_pk_mul_f32 v[64:65], v[66:67], v[64:65]
	v_fma_f32 v66, -v98, v99, 1.0
	v_fmac_f32_e32 v99, v66, v99
	v_div_scale_f32 v66, vcc, 1.0, v93, 1.0
	v_mul_f32_e32 v67, v66, v99
	v_fma_f32 v68, -v98, v67, v66
	v_fmac_f32_e32 v67, v68, v99
	v_div_scale_f32 v68, s[8:9], v92, v92, 1.0
	v_rcp_f32_e32 v69, v68
	v_fma_f32 v66, -v98, v67, v66
	v_div_fmas_f32 v66, v66, v99, v67
	v_div_fixup_f32 v67, v66, v93, 1.0
	v_fma_f32 v66, -v68, v69, 1.0
	v_fmac_f32_e32 v69, v66, v69
	v_div_scale_f32 v66, vcc, 1.0, v92, 1.0
	v_mul_f32_e32 v93, v66, v69
	v_fma_f32 v98, -v68, v93, v66
	v_fmac_f32_e32 v93, v98, v69
	v_fma_f32 v66, -v68, v93, v66
	v_div_fmas_f32 v66, v66, v69, v93
	v_div_fixup_f32 v66, v66, v92, 1.0
	v_pk_mul_f32 v[66:67], v[94:95], v[66:67]
	v_pk_add_f32 v[68:69], v[96:97], 1.0 op_sel_hi:[1,0]
	s_nop 0
	v_pk_mul_f32 v[66:67], v[68:69], v[66:67]
	v_and_b32_sdwa v68, v65, v90 dst_sel:DWORD dst_unused:UNUSED_PAD src0_sel:WORD_1 src1_sel:DWORD
	v_and_b32_sdwa v69, v64, v90 dst_sel:DWORD dst_unused:UNUSED_PAD src0_sel:WORD_1 src1_sel:DWORD
	v_add3_u32 v64, v64, v69, s3
	v_add3_u32 v65, v65, v68, s3
	v_and_b32_sdwa v68, v67, v90 dst_sel:DWORD dst_unused:UNUSED_PAD src0_sel:WORD_1 src1_sel:DWORD
	v_and_b32_sdwa v69, v66, v90 dst_sel:DWORD dst_unused:UNUSED_PAD src0_sel:WORD_1 src1_sel:DWORD
	v_add3_u32 v67, v67, v68, s3
	v_add3_u32 v66, v66, v69, s3
	v_and_b32_e32 v67, 0xffff0000, v67
	v_and_b32_e32 v66, 0xffff0000, v66
	v_or_b32_sdwa v65, v67, v65 dst_sel:DWORD dst_unused:UNUSED_PAD src0_sel:DWORD src1_sel:WORD_1
	v_or_b32_sdwa v64, v66, v64 dst_sel:DWORD dst_unused:UNUSED_PAD src0_sel:DWORD src1_sel:WORD_1
	global_store_dwordx2 v[70:71], v[64:65], off
